# dnprep T-solve rewritten: blocked 16x16 inverse (fwd-subst diag blocks + f32 MFMA off-diagonal chain), tables assembled in LDS, dwordx4 stores
# speedup vs baseline: 1.0316x; 1.0316x over previous
; __device__ __forceinline__ void phase_dnprep(KP kp_){ asm volatile("" : "+s"(kp_)); const Params p=load_params(kp_);
;   float* raw=(float*)smem;
;   float* tmp=(float*)(smem+34816);
;   char* qs=smem+67584;
;   char* ks=smem+84992;
;   float* Lf=(float*)(smem+102400);
;   float* Lb=(float*)(smem+118784);
;   float* sm=(float*)(smem+135168);
;   float *gcf=sm, *gcb=sm+64, *bef=sm+128, *beb=sm+192, *scl=sm+256;
;   const u16* R1=(const u16*)(p.ws+OFF_R1); const float* gates=(const float*)(p.ws+OFF_GATES);
;   u32x4 rp0,rp1,rp2; bool have_raw=false;
;   for (int item=blockIdx.x; item<2112; item+=gridDim.x){
;     int tid=threadIdx.x; asm volatile("" : "+v"(tid)); int lane=tid&63, wid=tid>>6;
;     int b,n,h,cidx,tok0,rs,re;
;     if (item<2048){ b=item>>10; n=(item>>3)&127; h=item&7; cidx=n+4; tok0=b*8192+n*64; rs=tok0; re=tok0+64; }
.LBB0_636:
	v_readlane_b32 s78, v253, 12
	v_readlane_b32 s79, v253, 13
	s_mov_b64 s[0:1], s[78:79]
	s_load_dwordx2 s[76:77], s[78:79], 0xf0
	v_readlane_b32 s75, v253, 6
	s_cmpk_gt_i32 s75, 0x83f
	s_cbranch_scc1 .LBB0_739
	s_load_dwordx4 s[16:19], s[0:1], 0xd8
	s_load_dwordx4 s[20:23], s[0:1], 0x40
	s_load_dwordx2 s[2:3], s[0:1], 0x50
	v_mbcnt_hi_u32_b32 v85, -1, v155
	v_mov_b32_e32 v0, 0x80
	s_waitcnt lgkmcnt(0)
	s_add_u32 s45, s18, 0x42bd000
	s_addc_u32 s46, s19, 0
	s_add_u32 s4, s18, 0x3da9000
	s_addc_u32 s5, s19, 0
	s_add_u32 s47, s18, 0x3fbd000
	s_addc_u32 s48, s19, 0
	s_add_u32 s24, s18, 0xa5bd000
	s_addc_u32 s25, s19, 0
	s_add_u32 s49, s18, 0x42bd800
	s_mov_b64 s[14:15], 0
	s_mov_b32 s44, 0xc000
	s_addc_u32 s50, s19, 0
	s_mov_b32 s19, 0
	s_movk_i32 s51, 0x1800
	s_mov_b32 s52, 0x41a00000
	s_mov_b32 s53, 0x3fb8aa3b
	s_mov_b32 s54, 0xc2ce8ed0
	s_mov_b32 s55, 0x42b17218
	s_mov_b32 s56, 0x7f800000
	s_mov_b32 s57, 0x3f2aaaab
	v_mov_b32_e32 v79, 0x3ecc95a3
	s_mov_b32 s58, 0x3f317218
	s_mov_b32 s59, 0x33800000
	s_mov_b32 s60, 0xbfb8aa3b
	s_mov_b32 s61, 0x42ce8ed0
	s_mov_b32 s62, 0xc2b17218
	v_mov_b32_e32 v1, 0
	s_movk_i32 s63, 0x6000
	s_movk_i32 s64, 0x440
	s_movk_i32 s65, 0x240
	s_mov_b32 s66, 0x800000
	s_mov_b32 s67, 0x10800
	s_movk_i32 s68, 0x1100
	s_movk_i32 s69, 0x110
	v_mov_b32_e32 v84, 0x7f800000
	v_mov_b32_e32 v80, 0x3f317218
	v_lshl_or_b32 v86, v85, 2, v0
	v_mov_b32_e32 v87, 0x3db504f3
	v_mov_b32_e32 v88, 0x1d000
	v_mov_b32_e32 v89, 0x19000
	s_mov_b32 s70, s75
	s_mov_b32 s71, s75
	s_branch .LBB0_640
.LBB0_639:
	s_or_b64 exec, exec, s[10:11]
	s_add_i32 s70, s70, s76
	s_andn2_b64 vcc, exec, s[14:15]
	s_mov_b64 s[14:15], -1
	s_cbranch_vccz .LBB0_739

; __device__ __forceinline__ void phase_dnprep(KP kp_){ asm volatile("" : "+s"(kp_)); const Params p=load_params(kp_);
;     ...
;         int jj=nt*16+r; float gfj=gcf[jj], gbj=gcb[jj];
;         _Pragma("unroll") for (int j=0;j<4;++j){ int i=mt*16+kg*4+j;
;           float ef=__expf(fminf(gcf[i]-gfj,0.f)), eb=__expf(fminf(gcb[i]-gbj,0.f));
;           float lf=(jj<i)?bef[i]*akk[j]*ef:0.f;
;           float af=(jj<=i)?aqk[j]*ef:0.f;
;           float lb=(jj>i)?beb[i]*akk[j]*eb:0.f;
;           float ab=(jj>=i)?aqk[j]*eb:0.f;
;           Lf[i*64+jj]=lf; Lb[(63-i)*64+(63-jj)]=lb;
;           *(u16*)(taf+16384+(i*64+jj)*2)=f2bf(af); *(u16*)(tab+16384+(i*64+jj)*2)=f2bf(ab); }
;       } }
;     __syncthreads();
;     if (wid<2){
;       int lbase = wid==0 ? 102400 : 118784; asm volatile("" : "+v"(lbase));
;       float Tc[64];
;       float4 lcur[16], lnxt[16];
;       _Pragma("unroll") for (int r4=0;r4<16;++r4){ lcur[r4]=make_float4(0.f,0.f,0.f,0.f); lnxt[r4]=lcur[r4]; }
;       _Pragma("unroll") for (int r=0;r<64;++r){
;         if (r+1<64){ _Pragma("unroll") for (int r4=0;r4<(r+1+3)/4;++r4) lnxt[r4]=*(const float4*)(smem+lbase+((r+1)*64+r4*4)*4); }
;         float a0=(r==lane)?1.f:0.f, a1=0.f, a2=0.f, a3=0.f;
;         _Pragma("unroll") for (int r4=0;r4<(r+3)/4;++r4){ float4 l=lcur[r4];
;           if (r4*4+0<r) a0-=l.x*Tc[r4*4+0]; if (r4*4+1<r) a1-=l.y*Tc[r4*4+1]; if (r4*4+2<r) a2-=l.z*Tc[r4*4+2]; if (r4*4+3<r) a3-=l.w*Tc[r4*4+3]; }
;         Tc[r]=(a0+a1)+(a2+a3);
.LBB0_734:
	s_or_b64 exec, exec, s[12:13]
	v_mul_f32_e32 v18, v19, v17
	v_or_b32_e32 v17, v45, v33
	v_mul_f32_e32 v2, v19, v2
	v_lshl_add_u32 v19, v17, 2, 0
	v_add_u32_e32 v19, 0x19000, v19
	ds_write_b32 v19, v16
	v_sub_u32_e32 v16, 0xfff, v17
	v_lshl_add_u32 v16, v16, 2, 0
	v_cvt_pk_bf16_f32 v2, v2, s0
	v_add_u32_e32 v16, 0x1d000, v16
	v_cndmask_b32_e64 v19, v2, 0, s[10:11]
	v_lshlrev_b32_e32 v2, 1, v17
	ds_write_b32 v16, v3
	v_ashrrev_i32_e32 v3, 31, v2
	v_lshl_add_u64 v[16:17], s[0:1], 0, v[2:3]
	flat_store_short v[16:17], v19
	v_cvt_pk_bf16_f32 v16, v18, s0
	v_cndmask_b32_e64 v16, v16, 0, vcc
	v_lshl_add_u64 v[2:3], s[34:35], 0, v[2:3]
	v_cmp_gt_i32_e32 vcc, 2, v0
	flat_store_short v[2:3], v16
	s_waitcnt lgkmcnt(0)
	s_barrier
	s_mov_b64 s[10:11], exec
	v_lshrrev_b32_e32 v32, 6, v154
	v_and_b32_e32 v33, 63, v154
	v_lshrrev_b32_e32 v34, 8, v154
	v_and_b32_e32 v36, 15, v154
	v_bfe_u32 v37, v154, 4, 2
	v_readfirstlane_b32 s0, v32
	s_lshr_b32 s1, s0, 2
	s_add_u32 s6, s0, s1
	s_and_b32 s6, s6, 3
	v_lshlrev_b32_e32 v35, 14, v34
	v_add_u32_e32 v35, 0x19000, v35
	v_lshlrev_b32_e32 v99, 8, v34
	v_sub_u32_e32 v99, 0x80, v99
	v_mul_u32_u24_e32 v42, 0x2800, v34
	s_cmp_eq_u32 s6, 3
	s_cbranch_scc1 .Lmy_ts_A
	v_mov_b32_e32 v38, s6
	v_mul_u32_u24_e32 v39, 0x1040, v38
	v_add_u32_e32 v94, v35, v39
	v_lshl_add_u32 v94, v36, 8, v94
	v_lshl_add_u32 v94, v37, 4, v94
	ds_read_b128 v[156:159], v94 offset:4096
	s_cmp_gt_u32 s6, 1
	s_cbranch_scc1 .Lmy_ts_skl
	ds_read_b128 v[160:163], v94 offset:8192
	ds_read_b128 v[164:167], v94 offset:8256
	s_cmp_gt_u32 s6, 0
	s_cbranch_scc1 .Lmy_ts_skl
	ds_read_b128 v[168:171], v94 offset:12288
	ds_read_b128 v[172:175], v94 offset:12352
	ds_read_b128 v[176:179], v94 offset:12416
.Lmy_ts_skl:
	v_lshlrev_b32_e32 v39, 4, v38
	v_add_u32_e32 v40, v39, v36
	v_lshl_add_u32 v39, v37, 2, v39
	v_lshlrev_b32_e32 v43, 7, v39
	v_lshl_add_u32 v43, v40, 1, v43
	v_sub_u32_e32 v44, 0x5ffe, v43
	v_cmp_eq_u32_e32 vcc, 1, v34
	v_lshlrev_b32_e32 v45, 2, v40
	v_sub_u32_e32 v46, 0x211fc, v45
	v_add_u32_e32 v45, 0x21000, v45
	v_cndmask_b32_e32 v97, v43, v44, vcc
	v_cndmask_b32_e32 v98, v45, v46, vcc
	ds_read_b32 v92, v98
	ds_read_b32 v93, v98 offset:512
	v_mul_u32_u24_e32 v39, 0x500, v38
	v_lshl_add_u32 v39, v36, 6, v39
	v_lshl_add_u32 v39, v36, 4, v39
	v_lshl_add_u32 v39, v37, 4, v39
	v_add_u32_e32 v95, v39, v42
	v_add_u32_e32 v95, 0x9c00, v95
	v_add_u32_e32 v96, 0xffffec00, v95
	s_waitcnt lgkmcnt(0)
	v_mul_f32_e32 v92, 0x3fb8aa3b, v92
	v_exp_f32_e32 v92, v92
	s_nop 0
	v_mul_f32_e32 v92, v93, v92
	s_branch .Lmy_ts_bar1
.Lmy_ts_A:
	v_lshlrev_b32_e32 v39, 4, v37
	v_lshlrev_b32_e32 v43, 7, v39
	v_lshl_add_u32 v43, v33, 1, v43
	v_sub_u32_e32 v44, 0x5ffe, v43
	v_cmp_eq_u32_e32 vcc, 1, v34
	v_lshlrev_b32_e32 v45, 2, v33
	v_sub_u32_e32 v46, 0x211fc, v45
	v_add_u32_e32 v45, 0x21000, v45
	v_cndmask_b32_e32 v97, v43, v44, vcc
	v_cndmask_b32_e32 v98, v45, v46, vcc
	ds_read_b32 v92, v98
	ds_read_b32 v93, v98 offset:512
	v_mul_u32_u24_e32 v39, 0x1040, v37
	v_add_u32_e32 v94, v35, v39
	ds_read_b128 v[156:159], v94 offset:256
	ds_read_b128 v[160:163], v94 offset:512
	ds_read_b128 v[164:167], v94 offset:768
	ds_read_b128 v[168:171], v94 offset:1024
	ds_read_b128 v[172:175], v94 offset:1280
	ds_read_b128 v[176:179], v94 offset:1296
	ds_read_b128 v[180:183], v94 offset:1536
	ds_read_b128 v[184:187], v94 offset:1552
	ds_read_b128 v[188:191], v94 offset:1792
	ds_read_b128 v[192:195], v94 offset:1808
	ds_read_b128 v[196:199], v94 offset:2048
	ds_read_b128 v[200:203], v94 offset:2064
	v_mul_u32_u24_e32 v39, 0x500, v37
	v_add_u32_e32 v39, v39, v42
	v_lshl_add_u32 v96, v36, 2, v39
	v_add_u32_e32 v96, 0x8800, v96
	v_lshl_add_u32 v95, v36, 6, v39
	v_lshl_add_u32 v95, v36, 4, v95
	v_add_u32_e32 v95, 0x9c00, v95
	v_cmp_eq_u32_e32 vcc, 0, v36
	s_nop 1
	v_cndmask_b32_e64 v48, 0, 1.0, vcc
	ds_read_b128 v[204:207], v94 offset:2304
	ds_read_b128 v[208:211], v94 offset:2320
	ds_read_b128 v[212:215], v94 offset:2336
	v_cmp_eq_u32_e32 vcc, 1, v36
	s_waitcnt lgkmcnt(14)
	s_nop 0
	v_cndmask_b32_e64 v64, 0, 1.0, vcc
	v_fma_f32 v49, -v156, v48, v64
	ds_read_b128 v[216:219], v94 offset:2560
	ds_read_b128 v[220:223], v94 offset:2576
	ds_read_b128 v[224:227], v94 offset:2592
	v_cmp_eq_u32_e32 vcc, 2, v36
	s_waitcnt lgkmcnt(15)
	s_nop 0
	v_cndmask_b32_e64 v64, 0, 1.0, vcc
	v_fma_f32 v64, -v160, v48, v64
	v_fma_f32 v50, -v161, v49, v64
	ds_read_b128 v[228:231], v94 offset:2816
	ds_read_b128 v[232:235], v94 offset:2832
	ds_read_b128 v[236:239], v94 offset:2848
	v_cmp_eq_u32_e32 vcc, 3, v36
	s_waitcnt lgkmcnt(15)
	v_mul_f32_e64 v65, -v165, v49
	v_cndmask_b32_e64 v64, 0, 1.0, vcc
	v_fma_f32 v64, -v164, v48, v64
	v_add_f32_e32 v68, v64, v65
	v_fma_f32 v51, -v166, v50, v68
	ds_read_b128 v[240:243], v94 offset:3072
	ds_read_b128 v[244:247], v94 offset:3088
	ds_read_b128 v[248:251], v94 offset:3104
	v_cmp_eq_u32_e32 vcc, 4, v36
	s_waitcnt lgkmcnt(15)
	v_mul_f32_e64 v65, -v169, v49
	v_mul_f32_e64 v66, -v170, v50
	v_cndmask_b32_e64 v64, 0, 1.0, vcc
	v_fma_f32 v64, -v168, v48, v64
	v_add_f32_e32 v68, v64, v65
	v_add_f32_e32 v68, v68, v66
	v_fma_f32 v52, -v171, v51, v68
	ds_read_b128 v[100:103], v94 offset:3328
	ds_read_b128 v[104:107], v94 offset:3344
	ds_read_b128 v[108:111], v94 offset:3360
	ds_read_b128 v[112:115], v94 offset:3376
	v_cmp_eq_u32_e32 vcc, 5, v36
	s_waitcnt lgkmcnt(15)
	v_mul_f32_e64 v65, -v173, v49
	v_mul_f32_e64 v66, -v174, v50
	v_mul_f32_e64 v67, -v175, v51
	v_cndmask_b32_e64 v64, 0, 1.0, vcc
	v_fma_f32 v64, -v172, v48, v64
	v_add_f32_e32 v68, v64, v65
	v_add_f32_e32 v69, v66, v67
	v_add_f32_e32 v68, v68, v69
	v_fma_f32 v53, -v176, v52, v68
	ds_read_b128 v[116:119], v94 offset:3584
	ds_read_b128 v[120:123], v94 offset:3600
	ds_read_b128 v[124:127], v94 offset:3616
	ds_read_b128 v[128:131], v94 offset:3632
	v_cmp_eq_u32_e32 vcc, 6, v36
	s_waitcnt lgkmcnt(15)
; __device__ __forceinline__ void phase_dnprep(KP kp_){ asm volatile("" : "+s"(kp_)); const Params p=load_params(kp_);
;     ...
;       _Pragma("unroll") for (int r=0;r<64;++r){
;         if (r+1<64){ _Pragma("unroll") for (int r4=0;r4<(r+1+3)/4;++r4) lnxt[r4]=*(const float4*)(smem+lbase+((r+1)*64+r4*4)*4); }
;         float a0=(r==lane)?1.f:0.f, a1=0.f, a2=0.f, a3=0.f;
;         _Pragma("unroll") for (int r4=0;r4<(r+3)/4;++r4){ float4 l=lcur[r4];
;           if (r4*4+0<r) a0-=l.x*Tc[r4*4+0]; if (r4*4+1<r) a1-=l.y*Tc[r4*4+1]; if (r4*4+2<r) a2-=l.z*Tc[r4*4+2]; if (r4*4+3<r) a3-=l.w*Tc[r4*4+3]; }
;         Tc[r]=(a0+a1)+(a2+a3);
	v_mul_f32_e64 v65, -v181, v49
	v_mul_f32_e64 v66, -v182, v50
	v_mul_f32_e64 v67, -v183, v51
	v_cndmask_b32_e64 v64, 0, 1.0, vcc
	v_fma_f32 v64, -v180, v48, v64
	v_fma_f32 v64, -v184, v52, v64
	v_add_f32_e32 v68, v64, v65
	v_add_f32_e32 v69, v66, v67
	v_add_f32_e32 v68, v68, v69
	v_fma_f32 v54, -v185, v53, v68
	ds_read_b128 v[132:135], v94 offset:3840
	ds_read_b128 v[136:139], v94 offset:3856
	ds_read_b128 v[140:143], v94 offset:3872
	ds_read_b128 v[144:147], v94 offset:3888
	v_cmp_eq_u32_e32 vcc, 7, v36
	s_waitcnt lgkmcnt(15)
	v_mul_f32_e64 v65, -v189, v49
	v_mul_f32_e64 v66, -v190, v50
	v_mul_f32_e64 v67, -v191, v51
	v_fma_f32 v65, -v193, v53, v65
	v_cndmask_b32_e64 v64, 0, 1.0, vcc
	v_fma_f32 v64, -v188, v48, v64
	v_fma_f32 v64, -v192, v52, v64
	v_add_f32_e32 v68, v64, v65
	v_add_f32_e32 v69, v66, v67
	v_add_f32_e32 v68, v68, v69
	v_fma_f32 v55, -v194, v54, v68
	v_cmp_eq_u32_e32 vcc, 8, v36
	s_waitcnt lgkmcnt(15)
	v_mul_f32_e64 v65, -v197, v49
	v_mul_f32_e64 v66, -v198, v50
	v_mul_f32_e64 v67, -v199, v51
	v_fma_f32 v65, -v201, v53, v65
	v_fma_f32 v66, -v202, v54, v66
	v_cndmask_b32_e64 v64, 0, 1.0, vcc
	v_fma_f32 v64, -v196, v48, v64
	v_fma_f32 v64, -v200, v52, v64
	v_add_f32_e32 v68, v64, v65
	v_add_f32_e32 v69, v66, v67
	v_add_f32_e32 v68, v68, v69
	v_fma_f32 v56, -v203, v55, v68
	v_cmp_eq_u32_e32 vcc, 9, v36
	s_waitcnt lgkmcnt(15)
	v_mul_f32_e64 v65, -v205, v49
	v_mul_f32_e64 v66, -v206, v50
	v_mul_f32_e64 v67, -v207, v51
	v_fma_f32 v65, -v209, v53, v65
	v_fma_f32 v66, -v210, v54, v66
	v_fma_f32 v67, -v211, v55, v67
	v_cndmask_b32_e64 v64, 0, 1.0, vcc
	v_fma_f32 v64, -v204, v48, v64
	v_fma_f32 v64, -v208, v52, v64
	v_add_f32_e32 v68, v64, v65
	v_add_f32_e32 v69, v66, v67
	v_add_f32_e32 v68, v68, v69
	v_fma_f32 v57, -v212, v56, v68
	v_cmp_eq_u32_e32 vcc, 10, v36
	s_waitcnt lgkmcnt(15)
	v_mul_f32_e64 v65, -v217, v49
	v_mul_f32_e64 v66, -v218, v50
	v_mul_f32_e64 v67, -v219, v51
	v_fma_f32 v65, -v221, v53, v65
	v_fma_f32 v66, -v222, v54, v66
	v_fma_f32 v67, -v223, v55, v67
	v_cndmask_b32_e64 v64, 0, 1.0, vcc
	v_fma_f32 v64, -v216, v48, v64
	v_fma_f32 v64, -v220, v52, v64
	v_fma_f32 v64, -v224, v56, v64
	v_add_f32_e32 v68, v64, v65
	v_add_f32_e32 v69, v66, v67
	v_add_f32_e32 v68, v68, v69
	v_fma_f32 v58, -v225, v57, v68
	v_cmp_eq_u32_e32 vcc, 11, v36
	s_waitcnt lgkmcnt(15)
	v_mul_f32_e64 v65, -v229, v49
	v_mul_f32_e64 v66, -v230, v50
	v_mul_f32_e64 v67, -v231, v51
	v_fma_f32 v65, -v233, v53, v65
	v_fma_f32 v66, -v234, v54, v66
	v_fma_f32 v67, -v235, v55, v67
	v_fma_f32 v65, -v237, v57, v65
	v_cndmask_b32_e64 v64, 0, 1.0, vcc
	v_fma_f32 v64, -v228, v48, v64
	v_fma_f32 v64, -v232, v52, v64
	v_fma_f32 v64, -v236, v56, v64
	v_add_f32_e32 v68, v64, v65
	v_add_f32_e32 v69, v66, v67
	v_add_f32_e32 v68, v68, v69
	v_fma_f32 v59, -v238, v58, v68
	v_cmp_eq_u32_e32 vcc, 12, v36
	s_waitcnt lgkmcnt(12)
	v_mul_f32_e64 v65, -v241, v49
	v_mul_f32_e64 v66, -v242, v50
	v_mul_f32_e64 v67, -v243, v51
	v_fma_f32 v65, -v245, v53, v65
	v_fma_f32 v66, -v246, v54, v66
	v_fma_f32 v67, -v247, v55, v67
	v_fma_f32 v65, -v249, v57, v65
	v_fma_f32 v66, -v250, v58, v66
	v_cndmask_b32_e64 v64, 0, 1.0, vcc
	v_fma_f32 v64, -v240, v48, v64
	v_fma_f32 v64, -v244, v52, v64
	v_fma_f32 v64, -v248, v56, v64
	v_add_f32_e32 v68, v64, v65
	v_add_f32_e32 v69, v66, v67
	v_add_f32_e32 v68, v68, v69
	v_fma_f32 v60, -v251, v59, v68
	v_cmp_eq_u32_e32 vcc, 13, v36
	s_waitcnt lgkmcnt(8)
	v_mul_f32_e64 v65, -v101, v49
	v_mul_f32_e64 v66, -v102, v50
	v_mul_f32_e64 v67, -v103, v51
	v_fma_f32 v65, -v105, v53, v65
	v_fma_f32 v66, -v106, v54, v66
	v_fma_f32 v67, -v107, v55, v67
	v_fma_f32 v65, -v109, v57, v65
	v_fma_f32 v66, -v110, v58, v66
	v_fma_f32 v67, -v111, v59, v67
	v_cndmask_b32_e64 v64, 0, 1.0, vcc
	v_fma_f32 v64, -v100, v48, v64
	v_fma_f32 v64, -v104, v52, v64
	v_fma_f32 v64, -v108, v56, v64
	v_add_f32_e32 v68, v64, v65
	v_add_f32_e32 v69, v66, v67
	v_add_f32_e32 v68, v68, v69
	v_fma_f32 v61, -v112, v60, v68
	v_cmp_eq_u32_e32 vcc, 14, v36
	s_waitcnt lgkmcnt(4)
	v_mul_f32_e64 v65, -v117, v49
	v_mul_f32_e64 v66, -v118, v50
	v_mul_f32_e64 v67, -v119, v51
	v_fma_f32 v65, -v121, v53, v65
	v_fma_f32 v66, -v122, v54, v66
	v_fma_f32 v67, -v123, v55, v67
	v_fma_f32 v65, -v125, v57, v65
	v_fma_f32 v66, -v126, v58, v66
	v_fma_f32 v67, -v127, v59, v67
	v_cndmask_b32_e64 v64, 0, 1.0, vcc
	v_fma_f32 v64, -v116, v48, v64
	v_fma_f32 v64, -v120, v52, v64
	v_fma_f32 v64, -v124, v56, v64
	v_fma_f32 v64, -v128, v60, v64
	v_add_f32_e32 v68, v64, v65
	v_add_f32_e32 v69, v66, v67
	v_add_f32_e32 v68, v68, v69
	v_fma_f32 v62, -v129, v61, v68
	v_cmp_eq_u32_e32 vcc, 15, v36
	s_waitcnt lgkmcnt(0)
; __device__ __forceinline__ void phase_dnprep(KP kp_){ asm volatile("" : "+s"(kp_)); const Params p=load_params(kp_);
;     ...
;       _Pragma("unroll") for (int r=0;r<64;++r){
;         if (r+1<64){ _Pragma("unroll") for (int r4=0;r4<(r+1+3)/4;++r4) lnxt[r4]=*(const float4*)(smem+lbase+((r+1)*64+r4*4)*4); }
;         float a0=(r==lane)?1.f:0.f, a1=0.f, a2=0.f, a3=0.f;
;         _Pragma("unroll") for (int r4=0;r4<(r+3)/4;++r4){ float4 l=lcur[r4];
;           if (r4*4+0<r) a0-=l.x*Tc[r4*4+0]; if (r4*4+1<r) a1-=l.y*Tc[r4*4+1]; if (r4*4+2<r) a2-=l.z*Tc[r4*4+2]; if (r4*4+3<r) a3-=l.w*Tc[r4*4+3]; }
;         Tc[r]=(a0+a1)+(a2+a3);
;         _Pragma("unroll") for (int r4=0;r4<16;++r4) lcur[r4]=lnxt[r4];
;         asm volatile("":::"memory"); }
;       if (wid==0){ int c=lane; float su=bef[c], sw=su*__expf(gcf[c]);
;         _Pragma("unroll") for (int r=0;r<64;++r){ *(u16*)(taf+(r*64+c)*2)=f2bf(Tc[r]*sw); *(u16*)(taf+8192+(r*64+c)*2)=f2bf(Tc[r]*su); } }
;       else { int j=63-lane; float su=beb[j], sw=su*__expf(gcb[j]);
;         _Pragma("unroll") for (int r=0;r<64;++r){ int i=63-r; *(u16*)(tab+(i*64+j)*2)=f2bf(Tc[r]*sw); *(u16*)(tab+8192+(i*64+j)*2)=f2bf(Tc[r]*su); } }
	v_mul_f32_e64 v65, -v133, v49
	v_mul_f32_e64 v66, -v134, v50
	v_mul_f32_e64 v67, -v135, v51
	v_fma_f32 v65, -v137, v53, v65
	v_fma_f32 v66, -v138, v54, v66
	v_fma_f32 v67, -v139, v55, v67
	v_fma_f32 v65, -v141, v57, v65
	v_fma_f32 v66, -v142, v58, v66
	v_fma_f32 v67, -v143, v59, v67
	v_fma_f32 v65, -v145, v61, v65
	v_cndmask_b32_e64 v64, 0, 1.0, vcc
	v_fma_f32 v64, -v132, v48, v64
	v_fma_f32 v64, -v136, v52, v64
	v_fma_f32 v64, -v140, v56, v64
	v_fma_f32 v64, -v144, v60, v64
	v_add_f32_e32 v68, v64, v65
	v_add_f32_e32 v69, v66, v67
	v_add_f32_e32 v68, v68, v69
	v_fma_f32 v63, -v146, v62, v68
	v_mul_f32_e32 v92, 0x3fb8aa3b, v92
	v_exp_f32_e32 v92, v92
	s_nop 0
	v_mul_f32_e32 v92, v93, v92
	ds_write_b32 v96, v48 offset:0
	ds_write_b32 v96, v49 offset:80
	ds_write_b32 v96, v50 offset:160
	ds_write_b32 v96, v51 offset:240
	ds_write_b32 v96, v52 offset:320
	ds_write_b32 v96, v53 offset:400
	ds_write_b32 v96, v54 offset:480
	ds_write_b32 v96, v55 offset:560
	ds_write_b32 v96, v56 offset:640
	ds_write_b32 v96, v57 offset:720
	ds_write_b32 v96, v58 offset:800
	ds_write_b32 v96, v59 offset:880
	ds_write_b32 v96, v60 offset:960
	ds_write_b32 v96, v61 offset:1040
	ds_write_b32 v96, v62 offset:1120
	ds_write_b32 v96, v63 offset:1200
	ds_write_b128 v95, v[48:51] offset:0
	ds_write_b128 v95, v[52:55] offset:16
	ds_write_b128 v95, v[56:59] offset:32
	ds_write_b128 v95, v[60:63] offset:48
	v_mul_f32_e32 v69, v48, v92
	v_mul_f32_e32 v70, v48, v93
	v_mad_i32_i24 v72, v99, 0, v97
	v_cvt_pk_bf16_f32 v71, v69, v70
	ds_write_b16 v72, v71
	ds_write_b16_d16_hi v72, v71 offset:8192
	v_mul_f32_e32 v69, v49, v92
	v_mul_f32_e32 v70, v49, v93
	v_mad_i32_i24 v72, v99, 1, v97
	v_cvt_pk_bf16_f32 v71, v69, v70
	ds_write_b16 v72, v71
	ds_write_b16_d16_hi v72, v71 offset:8192
	v_mul_f32_e32 v69, v50, v92
	v_mul_f32_e32 v70, v50, v93
	v_mad_i32_i24 v72, v99, 2, v97
	v_cvt_pk_bf16_f32 v71, v69, v70
	ds_write_b16 v72, v71
	ds_write_b16_d16_hi v72, v71 offset:8192
	v_mul_f32_e32 v69, v51, v92
	v_mul_f32_e32 v70, v51, v93
	v_mad_i32_i24 v72, v99, 3, v97
	v_cvt_pk_bf16_f32 v71, v69, v70
	ds_write_b16 v72, v71
	ds_write_b16_d16_hi v72, v71 offset:8192
	v_mul_f32_e32 v69, v52, v92
	v_mul_f32_e32 v70, v52, v93
	v_mad_i32_i24 v72, v99, 4, v97
	v_cvt_pk_bf16_f32 v71, v69, v70
	ds_write_b16 v72, v71
	ds_write_b16_d16_hi v72, v71 offset:8192
	v_mul_f32_e32 v69, v53, v92
	v_mul_f32_e32 v70, v53, v93
	v_mad_i32_i24 v72, v99, 5, v97
	v_cvt_pk_bf16_f32 v71, v69, v70
	ds_write_b16 v72, v71
	ds_write_b16_d16_hi v72, v71 offset:8192
	v_mul_f32_e32 v69, v54, v92
	v_mul_f32_e32 v70, v54, v93
	v_mad_i32_i24 v72, v99, 6, v97
	v_cvt_pk_bf16_f32 v71, v69, v70
	ds_write_b16 v72, v71
	ds_write_b16_d16_hi v72, v71 offset:8192
	v_mul_f32_e32 v69, v55, v92
	v_mul_f32_e32 v70, v55, v93
	v_mad_i32_i24 v72, v99, 7, v97
	v_cvt_pk_bf16_f32 v71, v69, v70
	ds_write_b16 v72, v71
	ds_write_b16_d16_hi v72, v71 offset:8192
	v_mul_f32_e32 v69, v56, v92
	v_mul_f32_e32 v70, v56, v93
	v_mad_i32_i24 v72, v99, 8, v97
	v_cvt_pk_bf16_f32 v71, v69, v70
	ds_write_b16 v72, v71
	ds_write_b16_d16_hi v72, v71 offset:8192
	v_mul_f32_e32 v69, v57, v92
	v_mul_f32_e32 v70, v57, v93
	v_mad_i32_i24 v72, v99, 9, v97
	v_cvt_pk_bf16_f32 v71, v69, v70
	ds_write_b16 v72, v71
	ds_write_b16_d16_hi v72, v71 offset:8192
	v_mul_f32_e32 v69, v58, v92
	v_mul_f32_e32 v70, v58, v93
	v_mad_i32_i24 v72, v99, 10, v97
	v_cvt_pk_bf16_f32 v71, v69, v70
	ds_write_b16 v72, v71
	ds_write_b16_d16_hi v72, v71 offset:8192
	v_mul_f32_e32 v69, v59, v92
	v_mul_f32_e32 v70, v59, v93
	v_mad_i32_i24 v72, v99, 11, v97
	v_cvt_pk_bf16_f32 v71, v69, v70
	ds_write_b16 v72, v71
	ds_write_b16_d16_hi v72, v71 offset:8192
	v_mul_f32_e32 v69, v60, v92
	v_mul_f32_e32 v70, v60, v93
	v_mad_i32_i24 v72, v99, 12, v97
	v_cvt_pk_bf16_f32 v71, v69, v70
	ds_write_b16 v72, v71
	ds_write_b16_d16_hi v72, v71 offset:8192
	v_mul_f32_e32 v69, v61, v92
	v_mul_f32_e32 v70, v61, v93
	v_mad_i32_i24 v72, v99, 13, v97
	v_cvt_pk_bf16_f32 v71, v69, v70
	ds_write_b16 v72, v71
	ds_write_b16_d16_hi v72, v71 offset:8192
	v_mul_f32_e32 v69, v62, v92
	v_mul_f32_e32 v70, v62, v93
	v_mad_i32_i24 v72, v99, 14, v97
	v_cvt_pk_bf16_f32 v71, v69, v70
	ds_write_b16 v72, v71
	ds_write_b16_d16_hi v72, v71 offset:8192
	v_mul_f32_e32 v69, v63, v92
	v_mul_f32_e32 v70, v63, v93
	v_mad_i32_i24 v72, v99, 15, v97
	v_cvt_pk_bf16_f32 v71, v69, v70
	ds_write_b16 v72, v71
	ds_write_b16_d16_hi v72, v71 offset:8192
; __device__ __forceinline__ void phase_dnprep(KP kp_){ asm volatile("" : "+s"(kp_)); const Params p=load_params(kp_);
;     ...
;     if (wid<2){
;       int lbase = wid==0 ? 102400 : 118784; asm volatile("" : "+v"(lbase));
;       float Tc[64];
;       float4 lcur[16], lnxt[16];
;       _Pragma("unroll") for (int r4=0;r4<16;++r4){ lcur[r4]=make_float4(0.f,0.f,0.f,0.f); lnxt[r4]=lcur[r4]; }
;       _Pragma("unroll") for (int r=0;r<64;++r){
;         if (r+1<64){ _Pragma("unroll") for (int r4=0;r4<(r+1+3)/4;++r4) lnxt[r4]=*(const float4*)(smem+lbase+((r+1)*64+r4*4)*4); }
;         float a0=(r==lane)?1.f:0.f, a1=0.f, a2=0.f, a3=0.f;
;         _Pragma("unroll") for (int r4=0;r4<(r+3)/4;++r4){ float4 l=lcur[r4];
;           if (r4*4+0<r) a0-=l.x*Tc[r4*4+0]; if (r4*4+1<r) a1-=l.y*Tc[r4*4+1]; if (r4*4+2<r) a2-=l.z*Tc[r4*4+2]; if (r4*4+3<r) a3-=l.w*Tc[r4*4+3]; }
;         Tc[r]=(a0+a1)+(a2+a3);
;         _Pragma("unroll") for (int r4=0;r4<16;++r4) lcur[r4]=lnxt[r4];
;         asm volatile("":::"memory"); }
;       if (wid==0){ int c=lane; float su=bef[c], sw=su*__expf(gcf[c]);
;         _Pragma("unroll") for (int r=0;r<64;++r){ *(u16*)(taf+(r*64+c)*2)=f2bf(Tc[r]*sw); *(u16*)(taf+8192+(r*64+c)*2)=f2bf(Tc[r]*su); } }
;       else { int j=63-lane; float su=beb[j], sw=su*__expf(gcb[j]);
;         _Pragma("unroll") for (int r=0;r<64;++r){ int i=63-r; *(u16*)(tab+(i*64+j)*2)=f2bf(Tc[r]*sw); *(u16*)(tab+8192+(i*64+j)*2)=f2bf(Tc[r]*su); } }
.Lmy_ts_bar1:
	s_waitcnt lgkmcnt(0)
	s_barrier
	s_cmp_eq_u32 s6, 3
	s_cbranch_scc1 .Lmy_ts_bar2
	ds_read_b128 v[180:183], v95
	ds_read_b128 v[184:187], v96 offset:1280
	ds_read_b128 v[188:191], v96 offset:2560
	ds_read_b128 v[192:195], v96 offset:3840
	s_waitcnt lgkmcnt(0)
	v_xor_b32_e32 v184, 0x80000000, v184
	v_xor_b32_e32 v185, 0x80000000, v185
	v_xor_b32_e32 v186, 0x80000000, v186
	v_xor_b32_e32 v187, 0x80000000, v187
	v_xor_b32_e32 v188, 0x80000000, v188
	v_xor_b32_e32 v189, 0x80000000, v189
	v_xor_b32_e32 v190, 0x80000000, v190
	v_xor_b32_e32 v191, 0x80000000, v191
	v_xor_b32_e32 v192, 0x80000000, v192
	v_xor_b32_e32 v193, 0x80000000, v193
	v_xor_b32_e32 v194, 0x80000000, v194
	v_xor_b32_e32 v195, 0x80000000, v195
	v_mfma_f32_16x16x4_f32 v[196:199], v156, v180, 0
	v_mfma_f32_16x16x4_f32 v[196:199], v157, v181, v[196:199]
	v_mfma_f32_16x16x4_f32 v[196:199], v158, v182, v[196:199]
	v_mfma_f32_16x16x4_f32 v[196:199], v159, v183, v[196:199]
	v_mfma_f32_16x16x4_f32 v[200:203], v160, v180, 0
	v_mfma_f32_16x16x4_f32 v[200:203], v161, v181, v[200:203]
	v_mfma_f32_16x16x4_f32 v[200:203], v162, v182, v[200:203]
	v_mfma_f32_16x16x4_f32 v[200:203], v163, v183, v[200:203]
	v_mfma_f32_16x16x4_f32 v[204:207], v168, v180, 0
	v_mfma_f32_16x16x4_f32 v[204:207], v169, v181, v[204:207]
	v_mfma_f32_16x16x4_f32 v[204:207], v170, v182, v[204:207]
	v_mfma_f32_16x16x4_f32 v[204:207], v171, v183, v[204:207]
	s_nop 1
	v_mfma_f32_16x16x4_f32 v[208:211], v184, v196, 0
	v_mfma_f32_16x16x4_f32 v[208:211], v185, v197, v[208:211]
	v_mfma_f32_16x16x4_f32 v[208:211], v186, v198, v[208:211]
	v_mfma_f32_16x16x4_f32 v[208:211], v187, v199, v[208:211]
	s_nop 9
	v_mfma_f32_16x16x4_f32 v[200:203], v164, v208, v[200:203]
	v_mfma_f32_16x16x4_f32 v[200:203], v165, v209, v[200:203]
	v_mfma_f32_16x16x4_f32 v[200:203], v166, v210, v[200:203]
	v_mfma_f32_16x16x4_f32 v[200:203], v167, v211, v[200:203]
	v_mfma_f32_16x16x4_f32 v[204:207], v172, v208, v[204:207]
	v_mfma_f32_16x16x4_f32 v[204:207], v173, v209, v[204:207]
	v_mfma_f32_16x16x4_f32 v[204:207], v174, v210, v[204:207]
	v_mfma_f32_16x16x4_f32 v[204:207], v175, v211, v[204:207]
	v_mul_f32_e32 v69, v208, v92
	v_mul_f32_e32 v70, v208, v93
	v_mad_i32_i24 v72, v99, 16, v97
	v_cvt_pk_bf16_f32 v71, v69, v70
	ds_write_b16 v72, v71
	ds_write_b16_d16_hi v72, v71 offset:8192
	v_mul_f32_e32 v69, v209, v92
	v_mul_f32_e32 v70, v209, v93
	v_mad_i32_i24 v72, v99, 17, v97
	v_cvt_pk_bf16_f32 v71, v69, v70
	ds_write_b16 v72, v71
	ds_write_b16_d16_hi v72, v71 offset:8192
	v_mul_f32_e32 v69, v210, v92
	v_mul_f32_e32 v70, v210, v93
	v_mad_i32_i24 v72, v99, 18, v97
	v_cvt_pk_bf16_f32 v71, v69, v70
	ds_write_b16 v72, v71
	ds_write_b16_d16_hi v72, v71 offset:8192
	v_mul_f32_e32 v69, v211, v92
	v_mul_f32_e32 v70, v211, v93
	v_mad_i32_i24 v72, v99, 19, v97
	v_cvt_pk_bf16_f32 v71, v69, v70
	ds_write_b16 v72, v71
	ds_write_b16_d16_hi v72, v71 offset:8192
	s_cmp_eq_u32 s6, 2
	s_cbranch_scc1 .Lmy_ts_bar2
	v_mfma_f32_16x16x4_f32 v[212:215], v188, v200, 0
	v_mfma_f32_16x16x4_f32 v[212:215], v189, v201, v[212:215]
	v_mfma_f32_16x16x4_f32 v[212:215], v190, v202, v[212:215]
	v_mfma_f32_16x16x4_f32 v[212:215], v191, v203, v[212:215]
	s_nop 9
	v_mfma_f32_16x16x4_f32 v[204:207], v176, v212, v[204:207]
	v_mfma_f32_16x16x4_f32 v[204:207], v177, v213, v[204:207]
	v_mfma_f32_16x16x4_f32 v[204:207], v178, v214, v[204:207]
	v_mfma_f32_16x16x4_f32 v[204:207], v179, v215, v[204:207]
	v_mul_f32_e32 v69, v212, v92
	v_mul_f32_e32 v70, v212, v93
	v_mad_i32_i24 v72, v99, 32, v97
	v_cvt_pk_bf16_f32 v71, v69, v70
	ds_write_b16 v72, v71
	ds_write_b16_d16_hi v72, v71 offset:8192
	v_mul_f32_e32 v69, v213, v92
	v_mul_f32_e32 v70, v213, v93
	v_mad_i32_i24 v72, v99, 33, v97
	v_cvt_pk_bf16_f32 v71, v69, v70
	ds_write_b16 v72, v71
	ds_write_b16_d16_hi v72, v71 offset:8192
	v_mul_f32_e32 v69, v214, v92
	v_mul_f32_e32 v70, v214, v93
	v_mad_i32_i24 v72, v99, 34, v97
	v_cvt_pk_bf16_f32 v71, v69, v70
	ds_write_b16 v72, v71
	ds_write_b16_d16_hi v72, v71 offset:8192
	v_mul_f32_e32 v69, v215, v92
	v_mul_f32_e32 v70, v215, v93
	v_mad_i32_i24 v72, v99, 35, v97
	v_cvt_pk_bf16_f32 v71, v69, v70
	ds_write_b16 v72, v71
	ds_write_b16_d16_hi v72, v71 offset:8192
	s_cmp_eq_u32 s6, 1
	s_cbranch_scc1 .Lmy_ts_bar2
	v_mfma_f32_16x16x4_f32 v[216:219], v192, v204, 0
	v_mfma_f32_16x16x4_f32 v[216:219], v193, v205, v[216:219]
	v_mfma_f32_16x16x4_f32 v[216:219], v194, v206, v[216:219]
	v_mfma_f32_16x16x4_f32 v[216:219], v195, v207, v[216:219]
	s_nop 9
	v_mul_f32_e32 v69, v216, v92
	v_mul_f32_e32 v70, v216, v93
	v_mad_i32_i24 v72, v99, 48, v97
	v_cvt_pk_bf16_f32 v71, v69, v70
	ds_write_b16 v72, v71
	ds_write_b16_d16_hi v72, v71 offset:8192
	v_mul_f32_e32 v69, v217, v92
	v_mul_f32_e32 v70, v217, v93
	v_mad_i32_i24 v72, v99, 49, v97
	v_cvt_pk_bf16_f32 v71, v69, v70
	ds_write_b16 v72, v71
	ds_write_b16_d16_hi v72, v71 offset:8192
	v_mul_f32_e32 v69, v218, v92
	v_mul_f32_e32 v70, v218, v93
	v_mad_i32_i24 v72, v99, 50, v97
	v_cvt_pk_bf16_f32 v71, v69, v70
	ds_write_b16 v72, v71
	ds_write_b16_d16_hi v72, v71 offset:8192
	v_mul_f32_e32 v69, v219, v92
	v_mul_f32_e32 v70, v219, v93
	v_mad_i32_i24 v72, v99, 51, v97
	v_cvt_pk_bf16_f32 v71, v69, v70
	ds_write_b16 v72, v71
	ds_write_b16_d16_hi v72, v71 offset:8192
.Lmy_ts_bar2:
	s_waitcnt lgkmcnt(0)
	s_barrier
	v_lshlrev_b32_e32 v73, 4, v154
	v_lshrrev_b32_e32 v75, 7, v154
	v_bfe_u32 v76, v154, 1, 2
	ds_read_b128 v[156:159], v73 offset:0
	ds_read_b128 v[160:163], v73 offset:8192
	ds_read_b128 v[164:167], v73 offset:16384
	ds_read_b128 v[168:171], v73 offset:24576
	v_cmp_gt_u32_e64 s[0:1], v76, v75
	v_cmp_lt_u32_e32 vcc, v76, v75
	v_add_u32_e32 v74, 0x2000, v73
	s_waitcnt lgkmcnt(0)
	v_cndmask_b32_e64 v156, v156, 0, s[0:1]
	v_cndmask_b32_e64 v157, v157, 0, s[0:1]
	v_cndmask_b32_e64 v158, v158, 0, s[0:1]
	v_cndmask_b32_e64 v159, v159, 0, s[0:1]
	v_cndmask_b32_e64 v160, v160, 0, s[0:1]
	v_cndmask_b32_e64 v161, v161, 0, s[0:1]
	v_cndmask_b32_e64 v162, v162, 0, s[0:1]
	v_cndmask_b32_e64 v163, v163, 0, s[0:1]
	v_cndmask_b32_e64 v164, v164, 0, vcc
	v_cndmask_b32_e64 v165, v165, 0, vcc
	v_cndmask_b32_e64 v166, v166, 0, vcc
	v_cndmask_b32_e64 v167, v167, 0, vcc
	v_cndmask_b32_e64 v168, v168, 0, vcc
	v_cndmask_b32_e64 v169, v169, 0, vcc
	v_cndmask_b32_e64 v170, v170, 0, vcc
	v_cndmask_b32_e64 v171, v171, 0, vcc
	global_store_dwordx4 v73, v[156:159], s[28:29]
	global_store_dwordx4 v74, v[160:163], s[28:29]
	global_store_dwordx4 v73, v[164:167], s[30:31]
	global_store_dwordx4 v74, v[168:171], s[30:31]
	s_branch .LBB0_639
